# tighter grid-barrier polling: s_sleep 1 in the 28 barrier poll loops replaced by s_nop 0
# baseline (speedup 1.0000x reference)
.LBB0_14:
	s_nop 0
	global_load_dword v2, v0, s[2:3] offset:32 sc1
	s_waitcnt vmcnt(0)
	v_and_b32_e32 v2, 0xffff0000, v2
	v_cmp_ne_u32_e32 vcc, v2, v1
	s_or_b64 s[4:5], vcc, s[4:5]
	s_andn2_b64 exec, exec, s[4:5]
	s_cbranch_execnz .LBB0_14

.LBB0_156:
	global_load_dword v15, v16, s[4:5] sc1
	s_waitcnt lgkmcnt(0)
	global_load_dword v0, v16, s[6:7] sc1
	global_load_dword v1, v16, s[8:9] sc1
	global_load_dword v2, v16, s[10:11] sc1
	global_load_dword v3, v16, s[12:13] sc1
	global_load_dword v4, v16, s[14:15] sc1
	global_load_dword v5, v16, s[20:21] sc1
	global_load_dword v6, v16, s[22:23] sc1
	global_load_dword v7, v16, s[24:25] sc1
	global_load_dword v8, v16, s[26:27] sc1
	global_load_dword v9, v16, s[28:29] sc1
	global_load_dword v10, v16, s[30:31] sc1
	global_load_dword v11, v16, s[34:35] sc1
	global_load_dword v12, v16, s[36:37] sc1
	global_load_dword v13, v16, s[38:39] sc1
	global_load_dword v14, v16, s[40:41] sc1
	s_mov_b64 s[42:43], -1
	s_mov_b64 s[44:45], -1
	s_waitcnt vmcnt(14)
	v_add_u32_e32 v17, v0, v15
	s_waitcnt vmcnt(13)
	v_add_u32_e32 v17, v17, v1
	s_waitcnt vmcnt(12)
	v_add_u32_e32 v17, v17, v2
	s_waitcnt vmcnt(11)
	v_add_u32_e32 v17, v17, v3
	s_waitcnt vmcnt(10)
	v_add_u32_e32 v17, v17, v4
	s_waitcnt vmcnt(9)
	v_add_u32_e32 v17, v17, v5
	s_waitcnt vmcnt(8)
	v_add_u32_e32 v17, v17, v6
	s_waitcnt vmcnt(7)
	v_add_u32_e32 v17, v17, v7
	s_waitcnt vmcnt(6)
	v_add_u32_e32 v17, v17, v8
	s_waitcnt vmcnt(5)
	v_add_u32_e32 v17, v17, v9
	s_waitcnt vmcnt(4)
	v_add_u32_e32 v17, v17, v10
	s_waitcnt vmcnt(3)
	v_add_u32_e32 v17, v17, v11
	s_waitcnt vmcnt(2)
	v_add_u32_e32 v17, v17, v12
	s_waitcnt vmcnt(1)
	v_add_u32_e32 v17, v17, v13
	s_waitcnt vmcnt(0)
	v_add_u32_e32 v17, v17, v14
	v_cmp_eq_u32_e32 vcc, s19, v17
	s_cbranch_vccnz .LBB0_155
	s_and_b32 s42, s33, 0xff
	s_cmp_eq_u32 s42, 0
	s_mov_b64 s[42:43], -1
	s_mov_b64 s[46:47], -1
	s_nop 0
	s_cbranch_scc0 .LBB0_160
	global_load_dword v17, v16, s[2:3] sc1
	s_waitcnt vmcnt(0)
	v_cmp_eq_u32_e32 vcc, 0, v17
	s_cbranch_vccnz .LBB0_162
	s_mov_b64 s[46:47], 0

.LBB0_174:
	s_and_b32 s22, s19, 0xff
	s_mov_b64 s[20:21], -1
	s_cmp_lg_u32 s22, 0
	s_mov_b64 s[24:25], -1
	s_nop 0
	s_cbranch_scc1 .LBB0_177
	global_load_dword v2, v0, s[8:9] sc1
	s_waitcnt vmcnt(0)
	v_cmp_eq_u32_e32 vcc, 0, v2
	s_cbranch_vccnz .LBB0_179
	s_mov_b64 s[24:25], 0
	s_mov_b64 s[22:23], -1

.LBB0_191:
	s_and_b32 s20, s19, 0xff
	s_cmp_lg_u32 s20, 0
	s_mov_b64 s[22:23], -1
	s_nop 0
	s_cbranch_scc1 .LBB0_194
	global_load_dword v1, v0, s[8:9] sc1
	s_waitcnt vmcnt(0)
	v_cmp_eq_u32_e32 vcc, 0, v1
	s_cbranch_vccnz .LBB0_196
	s_mov_b64 s[22:23], 0
	s_mov_b64 s[20:21], -1

.LBB0_637:
	global_load_dword v15, v16, s[4:5] sc1
	s_waitcnt lgkmcnt(0)
	global_load_dword v0, v16, s[6:7] sc1
	global_load_dword v1, v16, s[8:9] sc1
	global_load_dword v2, v16, s[10:11] sc1
	global_load_dword v3, v16, s[12:13] sc1
	global_load_dword v4, v16, s[14:15] sc1
	global_load_dword v5, v16, s[16:17] sc1
	global_load_dword v6, v16, s[18:19] sc1
	global_load_dword v7, v16, s[20:21] sc1
	global_load_dword v8, v16, s[22:23] sc1
	global_load_dword v9, v16, s[24:25] sc1
	global_load_dword v10, v16, s[26:27] sc1
	global_load_dword v11, v16, s[28:29] sc1
	global_load_dword v12, v16, s[30:31] sc1
	global_load_dword v13, v16, s[34:35] sc1
	global_load_dword v14, v16, s[36:37] sc1
	s_mov_b64 s[38:39], -1
	s_mov_b64 s[40:41], -1
	s_waitcnt vmcnt(14)
	v_add_u32_e32 v17, v0, v15
	s_waitcnt vmcnt(13)
	v_add_u32_e32 v17, v17, v1
	s_waitcnt vmcnt(12)
	v_add_u32_e32 v17, v17, v2
	s_waitcnt vmcnt(11)
	v_add_u32_e32 v17, v17, v3
	s_waitcnt vmcnt(10)
	v_add_u32_e32 v17, v17, v4
	s_waitcnt vmcnt(9)
	v_add_u32_e32 v17, v17, v5
	s_waitcnt vmcnt(8)
	v_add_u32_e32 v17, v17, v6
	s_waitcnt vmcnt(7)
	v_add_u32_e32 v17, v17, v7
	s_waitcnt vmcnt(6)
	v_add_u32_e32 v17, v17, v8
	s_waitcnt vmcnt(5)
	v_add_u32_e32 v17, v17, v9
	s_waitcnt vmcnt(4)
	v_add_u32_e32 v17, v17, v10
	s_waitcnt vmcnt(3)
	v_add_u32_e32 v17, v17, v11
	s_waitcnt vmcnt(2)
	v_add_u32_e32 v17, v17, v12
	s_waitcnt vmcnt(1)
	v_add_u32_e32 v17, v17, v13
	s_waitcnt vmcnt(0)
	v_add_u32_e32 v17, v17, v14
	v_cmp_eq_u32_e32 vcc, s33, v17
	s_cbranch_vccnz .LBB0_636
	s_and_b32 s38, s44, 0xff
	s_cmp_eq_u32 s38, 0
	s_mov_b64 s[38:39], -1
	s_mov_b64 s[42:43], -1
	s_nop 0
	s_cbranch_scc0 .LBB0_641
	global_load_dword v17, v16, s[2:3] sc1
	s_waitcnt vmcnt(0)
	v_cmp_eq_u32_e32 vcc, 0, v17
	s_cbranch_vccnz .LBB0_643
	s_mov_b64 s[42:43], 0

.LBB0_655:
	s_and_b32 s18, s22, 0xff
	s_mov_b64 s[16:17], -1
	s_cmp_lg_u32 s18, 0
	s_mov_b64 s[20:21], -1
	s_nop 0
	s_cbranch_scc1 .LBB0_658
	global_load_dword v2, v0, s[8:9] sc1
	s_waitcnt vmcnt(0)
	v_cmp_eq_u32_e32 vcc, 0, v2
	s_cbranch_vccnz .LBB0_660
	s_mov_b64 s[20:21], 0
	s_mov_b64 s[18:19], -1

.LBB0_672:
	s_and_b32 s16, s22, 0xff
	s_cmp_lg_u32 s16, 0
	s_mov_b64 s[18:19], -1
	s_nop 0
	s_cbranch_scc1 .LBB0_675
	global_load_dword v1, v0, s[8:9] sc1
	s_waitcnt vmcnt(0)
	v_cmp_eq_u32_e32 vcc, 0, v1
	s_cbranch_vccnz .LBB0_677
	s_mov_b64 s[18:19], 0
	s_mov_b64 s[16:17], -1

.LBB0_825:
	global_load_dword v15, v16, s[6:7] sc1
	s_waitcnt lgkmcnt(0)
	global_load_dword v0, v16, s[8:9] sc1
	global_load_dword v1, v16, s[10:11] sc1
	global_load_dword v2, v16, s[12:13] sc1
	global_load_dword v3, v16, s[14:15] sc1
	global_load_dword v4, v16, s[16:17] sc1
	global_load_dword v5, v16, s[18:19] sc1
	global_load_dword v6, v16, s[20:21] sc1
	global_load_dword v7, v16, s[22:23] sc1
	global_load_dword v8, v16, s[24:25] sc1
	global_load_dword v9, v16, s[26:27] sc1
	global_load_dword v10, v16, s[28:29] sc1
	global_load_dword v11, v16, s[30:31] sc1
	global_load_dword v12, v16, s[34:35] sc1
	global_load_dword v13, v16, s[36:37] sc1
	global_load_dword v14, v16, s[38:39] sc1
	s_mov_b64 s[40:41], -1
	s_mov_b64 s[42:43], -1
	s_waitcnt vmcnt(14)
	v_add_u32_e32 v17, v0, v15
	s_waitcnt vmcnt(13)
	v_add_u32_e32 v17, v17, v1
	s_waitcnt vmcnt(12)
	v_add_u32_e32 v17, v17, v2
	s_waitcnt vmcnt(11)
	v_add_u32_e32 v17, v17, v3
	s_waitcnt vmcnt(10)
	v_add_u32_e32 v17, v17, v4
	s_waitcnt vmcnt(9)
	v_add_u32_e32 v17, v17, v5
	s_waitcnt vmcnt(8)
	v_add_u32_e32 v17, v17, v6
	s_waitcnt vmcnt(7)
	v_add_u32_e32 v17, v17, v7
	s_waitcnt vmcnt(6)
	v_add_u32_e32 v17, v17, v8
	s_waitcnt vmcnt(5)
	v_add_u32_e32 v17, v17, v9
	s_waitcnt vmcnt(4)
	v_add_u32_e32 v17, v17, v10
	s_waitcnt vmcnt(3)
	v_add_u32_e32 v17, v17, v11
	s_waitcnt vmcnt(2)
	v_add_u32_e32 v17, v17, v12
	s_waitcnt vmcnt(1)
	v_add_u32_e32 v17, v17, v13
	s_waitcnt vmcnt(0)
	v_add_u32_e32 v17, v17, v14
	v_cmp_eq_u32_e32 vcc, s33, v17
	s_cbranch_vccnz .LBB0_824
	s_and_b32 s40, s46, 0xff
	s_cmp_eq_u32 s40, 0
	s_mov_b64 s[40:41], -1
	s_mov_b64 s[44:45], -1
	s_nop 0
	s_cbranch_scc0 .LBB0_829
	global_load_dword v17, v16, s[2:3] sc1
	s_waitcnt vmcnt(0)
	v_cmp_eq_u32_e32 vcc, 0, v17
	s_cbranch_vccnz .LBB0_831
	s_mov_b64 s[44:45], 0

.LBB0_843:
	s_and_b32 s20, s24, 0xff
	s_mov_b64 s[18:19], -1
	s_cmp_lg_u32 s20, 0
	s_mov_b64 s[22:23], -1
	s_nop 0
	s_cbranch_scc1 .LBB0_846
	global_load_dword v2, v0, s[10:11] sc1
	s_waitcnt vmcnt(0)
	v_cmp_eq_u32_e32 vcc, 0, v2
	s_cbranch_vccnz .LBB0_848
	s_mov_b64 s[22:23], 0
	s_mov_b64 s[20:21], -1

.LBB0_860:
	s_and_b32 s18, s24, 0xff
	s_cmp_lg_u32 s18, 0
	s_mov_b64 s[20:21], -1
	s_nop 0
	s_cbranch_scc1 .LBB0_863
	global_load_dword v1, v0, s[10:11] sc1
	s_waitcnt vmcnt(0)
	v_cmp_eq_u32_e32 vcc, 0, v1
	s_cbranch_vccnz .LBB0_865
	s_mov_b64 s[20:21], 0
	s_mov_b64 s[18:19], -1

.LBB0_992:
	global_load_dword v15, v16, s[4:5] sc1
	s_waitcnt lgkmcnt(0)
	global_load_dword v0, v16, s[8:9] sc1
	global_load_dword v1, v16, s[10:11] sc1
	global_load_dword v2, v16, s[12:13] sc1
	global_load_dword v3, v16, s[14:15] sc1
	global_load_dword v4, v16, s[16:17] sc1
	global_load_dword v5, v16, s[18:19] sc1
	global_load_dword v6, v16, s[20:21] sc1
	global_load_dword v7, v16, s[22:23] sc1
	global_load_dword v8, v16, s[24:25] sc1
	global_load_dword v9, v16, s[26:27] sc1
	global_load_dword v10, v16, s[28:29] sc1
	global_load_dword v11, v16, s[30:31] sc1
	global_load_dword v12, v16, s[34:35] sc1
	global_load_dword v13, v16, s[36:37] sc1
	global_load_dword v14, v16, s[38:39] sc1
	s_mov_b64 s[40:41], -1
	s_mov_b64 s[42:43], -1
	s_waitcnt vmcnt(14)
	v_add_u32_e32 v17, v0, v15
	s_waitcnt vmcnt(13)
	v_add_u32_e32 v17, v17, v1
	s_waitcnt vmcnt(12)
	v_add_u32_e32 v17, v17, v2
	s_waitcnt vmcnt(11)
	v_add_u32_e32 v17, v17, v3
	s_waitcnt vmcnt(10)
	v_add_u32_e32 v17, v17, v4
	s_waitcnt vmcnt(9)
	v_add_u32_e32 v17, v17, v5
	s_waitcnt vmcnt(8)
	v_add_u32_e32 v17, v17, v6
	s_waitcnt vmcnt(7)
	v_add_u32_e32 v17, v17, v7
	s_waitcnt vmcnt(6)
	v_add_u32_e32 v17, v17, v8
	s_waitcnt vmcnt(5)
	v_add_u32_e32 v17, v17, v9
	s_waitcnt vmcnt(4)
	v_add_u32_e32 v17, v17, v10
	s_waitcnt vmcnt(3)
	v_add_u32_e32 v17, v17, v11
	s_waitcnt vmcnt(2)
	v_add_u32_e32 v17, v17, v12
	s_waitcnt vmcnt(1)
	v_add_u32_e32 v17, v17, v13
	s_waitcnt vmcnt(0)
	v_add_u32_e32 v17, v17, v14
	v_cmp_eq_u32_e32 vcc, s33, v17
	s_cbranch_vccnz .LBB0_991
	s_and_b32 s40, s46, 0xff
	s_cmp_eq_u32 s40, 0
	s_mov_b64 s[40:41], -1
	s_mov_b64 s[44:45], -1
	s_nop 0
	s_cbranch_scc0 .LBB0_996
	global_load_dword v17, v16, s[2:3] sc1
	s_waitcnt vmcnt(0)
	v_cmp_eq_u32_e32 vcc, 0, v17
	s_cbranch_vccnz .LBB0_998
	s_mov_b64 s[44:45], 0
